# RWKV scan token loops (both passes) re-mapped to 8 keys x 1 value column per thread: 3-level 8-lane reductions, fewer VALU ops per token; pass-1 output reduction rides in the next token's reduction
# baseline (speedup 1.0000x reference)
; template <int pass>
; __device__ __forceinline__ void rw_item(const Params& p, int l, int seg, int h, LAS float* sm, int tid, int lane, int wave) {
;     ...
;     f32x2 sA[2], sB[2], pA[2], pB[2];
; #pragma unroll
;     for (int i = 0; i < 2; ++i) {
;         sA[i] = (f32x2){0.f, 0.f}; sB[i] = (f32x2){0.f, 0.f};
;         pA[i] = (f32x2){(kq * 4 + 2 * i == j0) ? 1.f : 0.f, (kq * 4 + 2 * i + 1 == j0) ? 1.f : 0.f};
;         pB[i] = (f32x2){(kq * 4 + 2 * i == j1) ? 1.f : 0.f, (kq * 4 + 2 * i + 1 == j1) ? 1.f : 0.f};
;     }
;     if (pass == 1 && seg > 0) {
;         const float* q = Lm + ((size_t)((seg - 1) * 6 + h) * 64 + j0) * 64 + kq * 4;
;         const f32x4 a = *(const f32x4*)q, b = *(const f32x4*)(q + 64);
;         sA[0] = a.xy; sA[1] = a.zw; sB[0] = b.xy; sB[1] = b.zw;
;     }
.LBB0_451:
	s_mul_hi_i32 s5, s57, 0x2aaaaaab
	s_lshr_b32 s4, s5, 31
	s_add_i32 s5, s5, s4
	s_mul_i32 s4, s5, 6
	v_ashrrev_i32_e32 v11, 3, v54
	s_sub_i32 s22, s57, s4
	v_and_b32_e32 v58, -2, v11
	v_mov_b32_e32 v2, 0
	s_andn2_b64 vcc, exec, s[8:9]
	v_mov_b32_e32 v3, 0
	v_mov_b32_e32 v4, 0
	v_mov_b32_e32 v5, 0
	v_mov_b32_e32 v6, 0
	v_mov_b32_e32 v7, 0
	v_mov_b32_e32 v8, 0
	v_mov_b32_e32 v9, 0
	v_mov_b32_e32 v104, 0
	v_mov_b32_e32 v105, 0
	v_mov_b32_e32 v106, 0
	v_mov_b32_e32 v107, 0
	v_mov_b32_e32 v108, 0
	v_mov_b32_e32 v109, 0
	v_mov_b32_e32 v110, 0
	v_mov_b32_e32 v111, 0
	s_cbranch_vccnz .LBB0_453
	s_add_i32 s4, s22, s4
	s_add_i32 s8, s4, -6
	s_ashr_i32 s9, s8, 31
	s_lshl_b64 s[8:9], s[8:9], 14
	v_ashrrev_i32_e32 v59, 31, v58
	s_add_u32 s8, s0, s8
	s_addc_u32 s9, s1, s9
	v_lshlrev_b64 v[2:3], 8, v[58:59]
	v_lshl_add_u64 v[2:3], s[8:9], 0, v[2:3]
	v_lshlrev_b32_e32 v0, 4, v10
	v_lshl_add_u64 v[2:3], v[2:3], 0, v[0:1]
	s_mov_b64 s[6:7], 0xef80000
	v_lshl_add_u64 v[4:5], v[2:3], 0, s[6:7]
	v_add_co_u32_e32 v2, vcc, 0xef80000, v2
	v_mov_b32_e32 v0, v12
	s_nop 0
	v_addc_co_u32_e32 v3, vcc, 0, v3, vcc
	global_load_dwordx4 v[6:9], v[2:3], off
	s_nop 0
	global_load_dwordx4 v[2:5], v[4:5], off offset:256
	v_and_b32_e32 v99, 7, v54
	v_lshrrev_b32_e32 v128, 3, v54
	v_lshlrev_b32_e32 v99, 5, v99
	v_lshl_add_u32 v99, v128, 8, v99
	s_add_i32 s6, s57, -6
	s_lshl_b32 s6, s6, 14
	v_add_u32_e32 v99, s6, v99
	v_add_u32_e32 v99, 0xef80000, v99
	global_load_dwordx4 v[104:107], v99, s[92:93]
	global_load_dwordx4 v[108:111], v99, s[92:93] offset:16

; #define LAS __attribute__((address_space(3)))
; template <int pass>
; __device__ __forceinline__ void rw_item(const Params& p, int l, int seg, int h, LAS float* sm, int tid, int lane, int wave) {
;     ...
;         float pf_rk[2] = {0.f, 0.f}; bf16_t pf_v[2] = {0, 0}, pf_g[2] = {0, 0};
;         if (pass == 1) {
; #pragma unroll
;             for (int rr = 0; rr < 2; ++rr) { const int tok = seg * SEG + sb * TS + wave + 8 * rr; const size_t g = (size_t)tok * RWW + h * 64 + lane; pf_rk[rr] = RK[(size_t)tok * 8 + h]; pf_v[rr] = Vv[g]; pf_g[rr] = Gg[g]; }
;         }
;         f32x4 nw4 = *(const LAS f32x4*)(bf + 1024 + kq * 4), nk4 = *(const LAS f32x4*)(bf + 2048 + kq * 4);
;         f32x4 na4 = *(const LAS f32x4*)(bf + 3072 + kq * 4), nb4 = *(const LAS f32x4*)(bf + 4096 + kq * 4);
;         f32x2 nvv = *(const LAS f32x2*)(bf + 5120 + j0);
;         f32x4 nq4 = (pass == 1) ? *(const LAS f32x4*)(bf + kq * 4) : (f32x4){0.f, 0.f, 0.f, 0.f};
; #pragma unroll 8
;         for (int t = 0; t < TS; ++t) {
;             const f32x4 w4 = nw4, k4 = nk4, a4 = na4, b4 = nb4, q4 = nq4; const f32x2 vv = nvv;
;             {
;                 const int tn = (t + 1 < TS) ? t + 1 : t, on = tn * 64 + kq * 4;
;                 nw4 = *(const LAS f32x4*)(bf + 1024 + on); nk4 = *(const LAS f32x4*)(bf + 2048 + on);
;                 na4 = *(const LAS f32x4*)(bf + 3072 + on); nb4 = *(const LAS f32x4*)(bf + 4096 + on);
;                 nvv = *(const LAS f32x2*)(bf + 5120 + tn * 64 + j0);
;                 if (pass == 1) nq4 = *(const LAS f32x4*)(bf + on);
;             }
;             const f32x2 vA = {vv.x, vv.x}, vB = {vv.y, vv.y};
;             f32x2 ua = b4.xy * sA[0], ub = b4.xy * sB[0];
;             ua = b4.zw * sA[1] + ua; ub = b4.zw * sB[1] + ub;
;             float uA = ua.x + ua.y, uB = ub.x + ub.y, gA = 0.f, gB = 0.f;
;             if (pass == 0) {
;                 f32x2 qa = b4.xy * pA[0], qb = b4.xy * pB[0];
;                 qa = b4.zw * pA[1] + qa; qb = b4.zw * pB[1] + qb;
;                 gA = qa.x + qa.y; gB = qb.x + qb.y;
;                 kq_sum16x4(uA, uB, gA, gB);
;             } else { uA = kq_sum<16>(uA); uB = kq_sum<16>(uB); }
;             const f32x2 uA2 = {uA, uA}, uB2 = {uB, uB};
;             { const f32x2 t0_ = k4.xy * vA - a4.xy * uA2, t1_ = k4.zw * vA - a4.zw * uA2; sA[0] = w4.xy * sA[0] + t0_; sA[1] = w4.zw * sA[1] + t1_; }
.LBB0_455:
	s_lshl_b32 s36, s30, 4
	s_add_i32 s0, s27, s36
	s_ashr_i32 s1, s0, 31
	v_mad_i64_i32 v[10:11], s[38:39], s0, v169, v[62:63]
	s_and_b32 s4, s30, 1
	s_lshl_b64 s[38:39], s[0:1], 5
	s_add_u32 s38, s28, s38
	s_addc_u32 s39, s29, s39
	v_lshlrev_b64 v[10:11], 1, v[10:11]
	s_add_i32 s0, s0, 8
	v_lshl_add_u64 v[12:13], s[16:17], 0, v[10:11]
	v_lshl_add_u64 v[10:11], s[12:13], 0, v[10:11]
	s_ashr_i32 s1, s0, 31
	global_load_dword v89, v1, s[38:39]
	global_load_ushort v90, v[12:13], off
	global_load_ushort v91, v[10:11], off
	v_mad_i64_i32 v[10:11], s[38:39], s0, v169, v[62:63]
	s_lshl_b64 s[0:1], s[0:1], 5
	s_add_u32 s0, s28, s0
	v_lshlrev_b64 v[10:11], 1, v[10:11]
	s_addc_u32 s1, s29, s1
	v_lshl_add_u64 v[12:13], s[16:17], 0, v[10:11]
	v_lshl_add_u64 v[10:11], s[12:13], 0, v[10:11]
	global_load_dword v86, v1, s[0:1]
	global_load_ushort v87, v[12:13], off
	global_load_ushort v88, v[10:11], off
	s_mul_i32 s0, s4, 0x6000
	s_add_i32 s5, s0, 0
	v_and_b32_e32 v99, 7, v54
	v_lshrrev_b32_e32 v128, 3, v54
	s_lshl_b32 s37, s4, 12
	v_cmp_eq_u32_e32 vcc, 0, v99
	v_lshl_add_u32 v129, v128, 2, s37
	v_lshl_add_u32 v99, v99, 5, s5
	v_lshl_add_u32 v128, v128, 2, s5
	ds_read_b128 v[184:187], v99 offset:16384
	ds_read_b128 v[188:191], v99 offset:16400
	ds_read_b128 v[192:195], v99 offset:12288
	ds_read_b128 v[196:199], v99 offset:12304
	ds_read_b128 v[200:203], v99 offset:8192
	ds_read_b128 v[204:207], v99 offset:8208
	ds_read_b128 v[208:211], v99 offset:4096
	ds_read_b128 v[212:215], v99 offset:4112
	ds_read_b128 v[176:179], v99 offset:0
	ds_read_b128 v[180:183], v99 offset:16
	ds_read_b32 v216, v128 offset:20480
	s_mov_b32 s38, 0
.LBB0_457:
	s_waitcnt lgkmcnt(0)
	ds_read_b128 v[120:123], v99 offset:16640
	ds_read_b128 v[124:127], v99 offset:16656
	ds_read_b128 v[218:221], v99 offset:12544
	ds_read_b128 v[222:225], v99 offset:12560
	ds_read_b128 v[226:229], v99 offset:8448
	ds_read_b128 v[230:233], v99 offset:8464
	ds_read_b128 v[234:237], v99 offset:4352
	ds_read_b128 v[238:241], v99 offset:4368
	ds_read_b128 v[112:115], v99 offset:256
	ds_read_b128 v[116:119], v99 offset:272
	ds_read_b32 v242, v128 offset:20736
	v_pk_mul_f32 v[244:245], v[184:185], v[104:105]
	v_pk_fma_f32 v[244:245], v[186:187], v[106:107], v[244:245]
	v_pk_fma_f32 v[244:245], v[188:189], v[108:109], v[244:245]
	v_pk_fma_f32 v[244:245], v[190:191], v[110:111], v[244:245]
	v_add_f32_e32 v244, v244, v245
	v_pk_mul_f32 v[200:201], v[200:201], v[216:217] op_sel_hi:[1,0]
	v_pk_mul_f32 v[202:203], v[202:203], v[216:217] op_sel_hi:[1,0]
	v_add_f32_dpp v244, v244, v244 quad_perm:[1,0,3,2] row_mask:0xf bank_mask:0xf bound_ctrl:1
	v_add_f32_dpp v102, v102, v102 quad_perm:[1,0,3,2] row_mask:0xf bank_mask:0xf bound_ctrl:1
	v_pk_mul_f32 v[204:205], v[204:205], v[216:217] op_sel_hi:[1,0]
	v_add_f32_dpp v244, v244, v244 quad_perm:[2,3,0,1] row_mask:0xf bank_mask:0xf bound_ctrl:1
	v_add_f32_dpp v102, v102, v102 quad_perm:[2,3,0,1] row_mask:0xf bank_mask:0xf bound_ctrl:1
	v_pk_mul_f32 v[206:207], v[206:207], v[216:217] op_sel_hi:[1,0]
	v_add_f32_dpp v244, v244, v244 row_half_mirror row_mask:0xf bank_mask:0xf bound_ctrl:1
	v_add_f32_dpp v102, v102, v102 row_half_mirror row_mask:0xf bank_mask:0xf bound_ctrl:1
	s_cmp_eq_u32 s38, 0
	s_cbranch_scc1 .Lmy_rw1_nowr
	s_mov_b64 exec, vcc
	ds_write_b32 v129, v102 offset:48896
	s_mov_b64 exec, -1
; #define LAS __attribute__((address_space(3)))
; template <int pass>
; __device__ __forceinline__ void rw_item(const Params& p, int l, int seg, int h, LAS float* sm, int tid, int lane, int wave) {
;     ...
;         for (int t = 0; t < TS; ++t) {
;             const f32x4 w4 = nw4, k4 = nk4, a4 = na4, b4 = nb4, q4 = nq4; const f32x2 vv = nvv;
;             {
;                 const int tn = (t + 1 < TS) ? t + 1 : t, on = tn * 64 + kq * 4;
;                 nw4 = *(const LAS f32x4*)(bf + 1024 + on); nk4 = *(const LAS f32x4*)(bf + 2048 + on);
;                 na4 = *(const LAS f32x4*)(bf + 3072 + on); nb4 = *(const LAS f32x4*)(bf + 4096 + on);
;                 nvv = *(const LAS f32x2*)(bf + 5120 + tn * 64 + j0);
;                 if (pass == 1) nq4 = *(const LAS f32x4*)(bf + on);
;             }
;             const f32x2 vA = {vv.x, vv.x}, vB = {vv.y, vv.y};
;             f32x2 ua = b4.xy * sA[0], ub = b4.xy * sB[0];
;             ua = b4.zw * sA[1] + ua; ub = b4.zw * sB[1] + ub;
;             float uA = ua.x + ua.y, uB = ub.x + ub.y, gA = 0.f, gB = 0.f;
;             if (pass == 0) {
;                 f32x2 qa = b4.xy * pA[0], qb = b4.xy * pB[0];
;                 qa = b4.zw * pA[1] + qa; qb = b4.zw * pB[1] + qb;
;                 gA = qa.x + qa.y; gB = qb.x + qb.y;
;                 kq_sum16x4(uA, uB, gA, gB);
;             } else { uA = kq_sum<16>(uA); uB = kq_sum<16>(uB); }
;             const f32x2 uA2 = {uA, uA}, uB2 = {uB, uB};
;             { const f32x2 t0_ = k4.xy * vA - a4.xy * uA2, t1_ = k4.zw * vA - a4.zw * uA2; sA[0] = w4.xy * sA[0] + t0_; sA[1] = w4.zw * sA[1] + t1_; }
;             { const f32x2 t0_ = k4.xy * vB - a4.xy * uB2, t1_ = k4.zw * vB - a4.zw * uB2; sB[0] = w4.xy * sB[0] + t0_; sB[1] = w4.zw * sB[1] + t1_; }
;             if (pass == 0) {
;                 const f32x2 gA2 = {gA, gA}, gB2 = {gB, gB};
;                 pA[0] = w4.xy * pA[0] - a4.xy * gA2; pA[1] = w4.zw * pA[1] - a4.zw * gA2;
;                 pB[0] = w4.xy * pB[0] - a4.xy * gB2; pB[1] = w4.zw * pB[1] - a4.zw * gB2;
;             } else {
;                 f32x2 oa = q4.xy * sA[0], ob2 = q4.xy * sB[0];
;                 oa = q4.zw * sA[1] + oa; ob2 = q4.zw * sB[1] + ob2;
;                 const float oA = kq_sum<16>(oa.x + oa.y), oB = kq_sum<16>(ob2.x + ob2.y);
;                 if (kq == 0) *(LAS f32x2*)(ob + t * 64 + j0) = (f32x2){oA, oB};
;             }
;         }
.Lmy_rw1_nowr:
	v_pk_fma_f32 v[200:201], v[192:193], v[244:245], v[200:201] op_sel_hi:[1,0,1] neg_lo:[1,0,0] neg_hi:[1,0,0]
	v_pk_fma_f32 v[202:203], v[194:195], v[244:245], v[202:203] op_sel_hi:[1,0,1] neg_lo:[1,0,0] neg_hi:[1,0,0]
	v_pk_fma_f32 v[204:205], v[196:197], v[244:245], v[204:205] op_sel_hi:[1,0,1] neg_lo:[1,0,0] neg_hi:[1,0,0]
	v_pk_fma_f32 v[206:207], v[198:199], v[244:245], v[206:207] op_sel_hi:[1,0,1] neg_lo:[1,0,0] neg_hi:[1,0,0]
	v_pk_fma_f32 v[104:105], v[208:209], v[104:105], v[200:201]
	v_pk_fma_f32 v[106:107], v[210:211], v[106:107], v[202:203]
	v_pk_fma_f32 v[108:109], v[212:213], v[108:109], v[204:205]
	v_pk_fma_f32 v[110:111], v[214:215], v[110:111], v[206:207]
	v_pk_mul_f32 v[102:103], v[176:177], v[104:105]
	v_pk_fma_f32 v[102:103], v[178:179], v[106:107], v[102:103]
	v_pk_fma_f32 v[102:103], v[180:181], v[108:109], v[102:103]
	v_pk_fma_f32 v[102:103], v[182:183], v[110:111], v[102:103]
	v_add_f32_e32 v102, v102, v103
	v_add_u32_e32 v99, 0x200, v99
	v_add_u32_e32 v128, 0x200, v128
	s_waitcnt lgkmcnt(0)
	ds_read_b128 v[184:187], v99 offset:16384
	ds_read_b128 v[188:191], v99 offset:16400
	ds_read_b128 v[192:195], v99 offset:12288
	ds_read_b128 v[196:199], v99 offset:12304
	ds_read_b128 v[200:203], v99 offset:8192
	ds_read_b128 v[204:207], v99 offset:8208
	ds_read_b128 v[208:211], v99 offset:4096
	ds_read_b128 v[212:215], v99 offset:4112
	ds_read_b128 v[176:179], v99 offset:0
	ds_read_b128 v[180:183], v99 offset:16
	ds_read_b32 v216, v128 offset:20480
	v_pk_mul_f32 v[244:245], v[120:121], v[104:105]
	v_pk_fma_f32 v[244:245], v[122:123], v[106:107], v[244:245]
	v_pk_fma_f32 v[244:245], v[124:125], v[108:109], v[244:245]
	v_pk_fma_f32 v[244:245], v[126:127], v[110:111], v[244:245]
	v_add_f32_e32 v244, v244, v245
	v_pk_mul_f32 v[226:227], v[226:227], v[242:243] op_sel_hi:[1,0]
	v_pk_mul_f32 v[228:229], v[228:229], v[242:243] op_sel_hi:[1,0]
	v_add_f32_dpp v244, v244, v244 quad_perm:[1,0,3,2] row_mask:0xf bank_mask:0xf bound_ctrl:1
	v_add_f32_dpp v102, v102, v102 quad_perm:[1,0,3,2] row_mask:0xf bank_mask:0xf bound_ctrl:1
	v_pk_mul_f32 v[230:231], v[230:231], v[242:243] op_sel_hi:[1,0]
	v_add_f32_dpp v244, v244, v244 quad_perm:[2,3,0,1] row_mask:0xf bank_mask:0xf bound_ctrl:1
	v_add_f32_dpp v102, v102, v102 quad_perm:[2,3,0,1] row_mask:0xf bank_mask:0xf bound_ctrl:1
	v_pk_mul_f32 v[232:233], v[232:233], v[242:243] op_sel_hi:[1,0]
	v_add_f32_dpp v244, v244, v244 row_half_mirror row_mask:0xf bank_mask:0xf bound_ctrl:1
	v_add_f32_dpp v102, v102, v102 row_half_mirror row_mask:0xf bank_mask:0xf bound_ctrl:1
	s_mov_b64 exec, vcc
	ds_write_b32 v129, v102 offset:49152
	s_mov_b64 exec, -1
	v_pk_fma_f32 v[226:227], v[218:219], v[244:245], v[226:227] op_sel_hi:[1,0,1] neg_lo:[1,0,0] neg_hi:[1,0,0]
	v_pk_fma_f32 v[228:229], v[220:221], v[244:245], v[228:229] op_sel_hi:[1,0,1] neg_lo:[1,0,0] neg_hi:[1,0,0]
	v_pk_fma_f32 v[230:231], v[222:223], v[244:245], v[230:231] op_sel_hi:[1,0,1] neg_lo:[1,0,0] neg_hi:[1,0,0]
	v_pk_fma_f32 v[232:233], v[224:225], v[244:245], v[232:233] op_sel_hi:[1,0,1] neg_lo:[1,0,0] neg_hi:[1,0,0]
	v_pk_fma_f32 v[104:105], v[234:235], v[104:105], v[226:227]
	v_pk_fma_f32 v[106:107], v[236:237], v[106:107], v[228:229]
	v_pk_fma_f32 v[108:109], v[238:239], v[108:109], v[230:231]
	v_pk_fma_f32 v[110:111], v[240:241], v[110:111], v[232:233]
	v_pk_mul_f32 v[102:103], v[112:113], v[104:105]
	v_pk_fma_f32 v[102:103], v[114:115], v[106:107], v[102:103]
	v_pk_fma_f32 v[102:103], v[116:117], v[108:109], v[102:103]
	v_pk_fma_f32 v[102:103], v[118:119], v[110:111], v[102:103]
	v_add_f32_e32 v102, v102, v103
	v_add_u32_e32 v129, 0x200, v129
	s_add_i32 s38, s38, 1
	s_cmp_lg_u32 s38, 8
	s_cbranch_scc1 .LBB0_457
	s_nop 1
	v_add_f32_dpp v102, v102, v102 quad_perm:[1,0,3,2] row_mask:0xf bank_mask:0xf bound_ctrl:1
	s_nop 1
	v_add_f32_dpp v102, v102, v102 quad_perm:[2,3,0,1] row_mask:0xf bank_mask:0xf bound_ctrl:1
	s_nop 1
	v_add_f32_dpp v102, v102, v102 row_half_mirror row_mask:0xf bank_mask:0xf bound_ctrl:1
	s_mov_b64 exec, vcc
	ds_write_b32 v129, v102 offset:48896
	s_mov_b64 exec, -1
